# combined: conv arithmetic in alpha A from stage registers (no copies), P4 rows XCD-local, accumulator zeroing with v_pk_mov_b32
# baseline (speedup 1.0000x reference)
.LBB0_187:
	s_ashr_i32 s47, s46, 31
	s_lshl_b64 s[48:49], s[46:47], 19
	s_add_u32 s48, s8, s48
	s_addc_u32 s49, s9, s49
	s_and_b64 s[50:51], s[6:7], exec
	s_cselect_b32 s47, s49, s55
	s_cselect_b32 s53, s48, s54
	s_ashr_i32 s45, s44, 31
	s_lshl_b64 s[50:51], s[44:45], 19
	s_add_u32 s50, s60, s50
	s_addc_u32 s51, s61, s51
	s_and_b64 s[58:59], s[6:7], exec
	s_cselect_b32 s45, s51, s57
	s_cselect_b32 s95, s50, s56
	s_add_u32 s54, s54, 0x40080
	s_addc_u32 s55, s55, 0
	s_add_u32 s96, s56, 0x100
	v_mov_b32_e32 v0, 0
	v_mov_b32_e32 v1, v0
	v_pk_mov_b32 v[2:3], v[0:1], v[0:1]
	v_pk_mov_b32 v[4:5], v[0:1], v[0:1]
	v_pk_mov_b32 v[6:7], v[0:1], v[0:1]
	v_pk_mov_b32 v[8:9], v[0:1], v[0:1]
	v_pk_mov_b32 v[10:11], v[0:1], v[0:1]
	v_pk_mov_b32 v[12:13], v[0:1], v[0:1]
	v_pk_mov_b32 v[14:15], v[0:1], v[0:1]
	v_pk_mov_b32 v[16:17], v[0:1], v[0:1]
	v_pk_mov_b32 v[18:19], v[0:1], v[0:1]
	v_pk_mov_b32 v[20:21], v[0:1], v[0:1]
	v_pk_mov_b32 v[22:23], v[0:1], v[0:1]
	v_pk_mov_b32 v[24:25], v[0:1], v[0:1]
	v_pk_mov_b32 v[26:27], v[0:1], v[0:1]
	v_pk_mov_b32 v[28:29], v[0:1], v[0:1]
	v_pk_mov_b32 v[30:31], v[0:1], v[0:1]
	v_pk_mov_b32 v[32:33], v[0:1], v[0:1]
	v_pk_mov_b32 v[34:35], v[0:1], v[0:1]
	v_pk_mov_b32 v[36:37], v[0:1], v[0:1]
	v_pk_mov_b32 v[38:39], v[0:1], v[0:1]
	v_pk_mov_b32 v[40:41], v[0:1], v[0:1]
	v_pk_mov_b32 v[42:43], v[0:1], v[0:1]
	v_pk_mov_b32 v[44:45], v[0:1], v[0:1]
	v_pk_mov_b32 v[46:47], v[0:1], v[0:1]
	v_pk_mov_b32 v[48:49], v[0:1], v[0:1]
	v_pk_mov_b32 v[50:51], v[0:1], v[0:1]
	v_pk_mov_b32 v[52:53], v[0:1], v[0:1]
	v_pk_mov_b32 v[54:55], v[0:1], v[0:1]
	v_pk_mov_b32 v[56:57], v[0:1], v[0:1]
	v_pk_mov_b32 v[58:59], v[0:1], v[0:1]
	v_pk_mov_b32 v[60:61], v[0:1], v[0:1]
	v_pk_mov_b32 v[62:63], v[0:1], v[0:1]
	v_pk_mov_b32 v[64:65], v[0:1], v[0:1]
	v_pk_mov_b32 v[66:67], v[0:1], v[0:1]
	v_pk_mov_b32 v[68:69], v[0:1], v[0:1]
	v_pk_mov_b32 v[70:71], v[0:1], v[0:1]
	v_pk_mov_b32 v[72:73], v[0:1], v[0:1]
	v_pk_mov_b32 v[74:75], v[0:1], v[0:1]
	v_pk_mov_b32 v[76:77], v[0:1], v[0:1]
	v_pk_mov_b32 v[78:79], v[0:1], v[0:1]
	v_pk_mov_b32 v[80:81], v[0:1], v[0:1]
	v_pk_mov_b32 v[82:83], v[0:1], v[0:1]
	v_pk_mov_b32 v[84:85], v[0:1], v[0:1]
	v_pk_mov_b32 v[86:87], v[0:1], v[0:1]
	v_pk_mov_b32 v[88:89], v[0:1], v[0:1]
	v_pk_mov_b32 v[90:91], v[0:1], v[0:1]
	v_pk_mov_b32 v[92:93], v[0:1], v[0:1]
	v_pk_mov_b32 v[94:95], v[0:1], v[0:1]
	v_pk_mov_b32 v[96:97], v[0:1], v[0:1]
	v_pk_mov_b32 v[98:99], v[0:1], v[0:1]
	v_pk_mov_b32 v[100:101], v[0:1], v[0:1]
	v_pk_mov_b32 v[102:103], v[0:1], v[0:1]
	v_pk_mov_b32 v[104:105], v[0:1], v[0:1]
	v_pk_mov_b32 v[106:107], v[0:1], v[0:1]
	v_pk_mov_b32 v[108:109], v[0:1], v[0:1]
	v_pk_mov_b32 v[110:111], v[0:1], v[0:1]
	v_pk_mov_b32 v[112:113], v[0:1], v[0:1]
	v_pk_mov_b32 v[114:115], v[0:1], v[0:1]
	v_pk_mov_b32 v[116:117], v[0:1], v[0:1]
	v_pk_mov_b32 v[118:119], v[0:1], v[0:1]
	v_pk_mov_b32 v[120:121], v[0:1], v[0:1]
	v_pk_mov_b32 v[122:123], v[0:1], v[0:1]
	v_pk_mov_b32 v[124:125], v[0:1], v[0:1]
	v_pk_mov_b32 v[126:127], v[0:1], v[0:1]
	s_addc_u32 s97, s57, 0
	s_mov_b32 s98, -2

.LBB0_484:
	s_ashr_i32 s37, s36, 31
	s_lshl_b64 s[38:39], s[36:37], 20
	s_add_u32 s38, s33, s38
	s_addc_u32 s39, s50, s39
	s_and_b64 s[40:41], s[6:7], exec
	s_cselect_b32 s9, s39, s45
	s_cselect_b32 s37, s38, s44
	s_ashr_i32 s35, s34, 31
	s_lshl_b64 s[40:41], s[34:35], 20
	s_add_u32 s40, s51, s40
	s_addc_u32 s41, s52, s41
	s_and_b64 s[48:49], s[6:7], exec
	s_cselect_b32 s35, s41, s47
	s_cselect_b32 s43, s40, s46
	s_add_u32 s44, s44, 0x80080
	s_addc_u32 s45, s45, 0
	s_add_u32 s69, s46, 0x100
	v_mov_b32_e32 v0, 0
	v_mov_b32_e32 v1, v0
	v_pk_mov_b32 v[2:3], v[0:1], v[0:1]
	v_pk_mov_b32 v[4:5], v[0:1], v[0:1]
	v_pk_mov_b32 v[6:7], v[0:1], v[0:1]
	v_pk_mov_b32 v[8:9], v[0:1], v[0:1]
	v_pk_mov_b32 v[10:11], v[0:1], v[0:1]
	v_pk_mov_b32 v[12:13], v[0:1], v[0:1]
	v_pk_mov_b32 v[14:15], v[0:1], v[0:1]
	v_pk_mov_b32 v[16:17], v[0:1], v[0:1]
	v_pk_mov_b32 v[18:19], v[0:1], v[0:1]
	v_pk_mov_b32 v[20:21], v[0:1], v[0:1]
	v_pk_mov_b32 v[22:23], v[0:1], v[0:1]
	v_pk_mov_b32 v[24:25], v[0:1], v[0:1]
	v_pk_mov_b32 v[26:27], v[0:1], v[0:1]
	v_pk_mov_b32 v[28:29], v[0:1], v[0:1]
	v_pk_mov_b32 v[30:31], v[0:1], v[0:1]
	v_pk_mov_b32 v[32:33], v[0:1], v[0:1]
	v_pk_mov_b32 v[34:35], v[0:1], v[0:1]
	v_pk_mov_b32 v[36:37], v[0:1], v[0:1]
	v_pk_mov_b32 v[38:39], v[0:1], v[0:1]
	v_pk_mov_b32 v[40:41], v[0:1], v[0:1]
	v_pk_mov_b32 v[42:43], v[0:1], v[0:1]
	v_pk_mov_b32 v[44:45], v[0:1], v[0:1]
	v_pk_mov_b32 v[46:47], v[0:1], v[0:1]
	v_pk_mov_b32 v[48:49], v[0:1], v[0:1]
	v_pk_mov_b32 v[50:51], v[0:1], v[0:1]
	v_pk_mov_b32 v[52:53], v[0:1], v[0:1]
	v_pk_mov_b32 v[54:55], v[0:1], v[0:1]
	v_pk_mov_b32 v[56:57], v[0:1], v[0:1]
	v_pk_mov_b32 v[58:59], v[0:1], v[0:1]
	v_pk_mov_b32 v[60:61], v[0:1], v[0:1]
	v_pk_mov_b32 v[62:63], v[0:1], v[0:1]
	v_pk_mov_b32 v[64:65], v[0:1], v[0:1]
	v_pk_mov_b32 v[66:67], v[0:1], v[0:1]
	v_pk_mov_b32 v[68:69], v[0:1], v[0:1]
	v_pk_mov_b32 v[70:71], v[0:1], v[0:1]
	v_pk_mov_b32 v[72:73], v[0:1], v[0:1]
	v_pk_mov_b32 v[74:75], v[0:1], v[0:1]
	v_pk_mov_b32 v[76:77], v[0:1], v[0:1]
	v_pk_mov_b32 v[78:79], v[0:1], v[0:1]
	v_pk_mov_b32 v[80:81], v[0:1], v[0:1]
	v_pk_mov_b32 v[82:83], v[0:1], v[0:1]
	v_pk_mov_b32 v[84:85], v[0:1], v[0:1]
	v_pk_mov_b32 v[86:87], v[0:1], v[0:1]
	v_pk_mov_b32 v[88:89], v[0:1], v[0:1]
	v_pk_mov_b32 v[90:91], v[0:1], v[0:1]
	v_pk_mov_b32 v[92:93], v[0:1], v[0:1]
	v_pk_mov_b32 v[94:95], v[0:1], v[0:1]
	v_pk_mov_b32 v[96:97], v[0:1], v[0:1]
	v_pk_mov_b32 v[98:99], v[0:1], v[0:1]
	v_pk_mov_b32 v[100:101], v[0:1], v[0:1]
	v_pk_mov_b32 v[102:103], v[0:1], v[0:1]
	v_pk_mov_b32 v[104:105], v[0:1], v[0:1]
	v_pk_mov_b32 v[106:107], v[0:1], v[0:1]
	v_pk_mov_b32 v[108:109], v[0:1], v[0:1]
	v_pk_mov_b32 v[110:111], v[0:1], v[0:1]
	v_pk_mov_b32 v[112:113], v[0:1], v[0:1]
	v_pk_mov_b32 v[114:115], v[0:1], v[0:1]
	v_pk_mov_b32 v[116:117], v[0:1], v[0:1]
	v_pk_mov_b32 v[118:119], v[0:1], v[0:1]
	v_pk_mov_b32 v[120:121], v[0:1], v[0:1]
	v_pk_mov_b32 v[122:123], v[0:1], v[0:1]
	v_pk_mov_b32 v[124:125], v[0:1], v[0:1]
	v_pk_mov_b32 v[126:127], v[0:1], v[0:1]
	s_addc_u32 s70, s47, 0
	s_mov_b32 s71, -2
